# v036 + HGRN: end-of-chunk vmcnt(0) becomes vmcnt(2) on waves 4-7 so they no longer wait for their own output-store acks every chunk
# speedup vs baseline: 1.0102x; 1.0102x over previous
; #define LAS __attribute__((address_space(3)))
; __device__ __forceinline__ unsigned pkbf(float lo, float hi) { typedef __bf16 b2 __attribute__((ext_vector_type(2))); f32x2 v = {lo, hi}; b2 b = __builtin_convertvector(v, b2); return __builtin_bit_cast(unsigned, b); }
; #define MFMA32(a, b, c) __builtin_amdgcn_mfma_f32_32x32x16_bf16((a), (b), (c), 0, 0, 0)
; __device__ __forceinline__ s16x4 trrd(LAS const unsigned char* p) { return __builtin_bit_cast(s16x4, __builtin_amdgcn_ds_read_tr16_b64_v4i16((LAS v4i16_t*)p)); }
; __device__ __forceinline__ bf16x8 cat8(s16x4 lo, s16x4 hi) { return (bf16x8){lo[0], lo[1], lo[2], lo[3], hi[0], hi[1], hi[2], hi[3]}; }
; __device__ __forceinline__ void hgrn_phase(LAS unsigned char* lds, const bf16_t* mix, bf16_t* OFB, int item) {
;     ...
;         { const int kb = wid >> 1, vb = wid & 1;
; #pragma unroll
;           for (int i4 = 0; i4 < 4; ++i4) { const f32x4 eg = *(LAS const f32x4*)(lds + HG_EGL + (32 * kb + 8 * i4 + 4 * h) * 4);
;               sacc[4 * i4] *= eg[0]; sacc[4 * i4 + 1] *= eg[1]; sacc[4 * i4 + 2] *= eg[2]; sacc[4 * i4 + 3] *= eg[3]; }
;           { bf16x8 Af[4], Bf[4];
; #pragma unroll
;             for (int ks = 0; ks < 4; ++ks) {
;                 LAS const unsigned char* ap = lds + HG_KD + (16 * ks + trr) * HG_KDP + (32 * kb + trc) * 2;
;                 LAS const unsigned char* bp = lds + HG_V + (16 * ks + trr) * HG_VP + (32 * vb + trc) * 2;
;                 Af[ks] = cat8(trrd(ap), trrd(ap + 4 * HG_KDP)); Bf[ks] = cat8(trrd(bp), trrd(bp + 4 * HG_VP)); }
; #pragma unroll
;             for (int ks = 0; ks < 4; ++ks) sacc = MFMA32(Af[ks], Bf[ks], sacc); }
; #pragma unroll
;           for (int i4 = 0; i4 < 4; ++i4) { u32x2 w; w.x = pkbf(sacc[4 * i4], sacc[4 * i4 + 1]); w.y = pkbf(sacc[4 * i4 + 2], sacc[4 * i4 + 3]);
;               *(LAS u32x2*)(lds + HG_ST + (32 * vb + r) * HG_P + (32 * kb + 8 * i4 + 4 * h) * 2) = w; } }
; #pragma unroll
;         for (int j = 0; j < 8; ++j) { cq[j] = nq[j]; ck[j] = nk[j]; }
;         cvv = nv;
.LBB0_506:
	v_add_u32_e32 v1, s66, v54
	ds_read_b128 v[2:5], v1
	ds_read_b128 v[6:9], v1 offset:32
	ds_read_b128 v[10:13], v1 offset:64
	s_nop 0
	ds_read_b128 v[32:35], v1 offset:96
	ds_read_b64_tr_b16 v[36:37], v84 offset:52224
	ds_read_b64_tr_b16 v[38:39], v84 offset:53504
	ds_read_b64_tr_b16 v[40:41], v85
	ds_read_b64_tr_b16 v[42:43], v85 offset:768
	s_waitcnt lgkmcnt(4)
	v_pk_mul_f32 v[28:29], v[28:29], v[32:33]
	v_pk_mul_f32 v[24:25], v[24:25], v[10:11]
	v_pk_mul_f32 v[20:21], v[20:21], v[6:7]
	v_pk_mul_f32 v[16:17], v[16:17], v[2:3]
	v_pk_mul_f32 v[30:31], v[30:31], v[34:35]
	v_pk_mul_f32 v[26:27], v[26:27], v[12:13]
	v_pk_mul_f32 v[22:23], v[22:23], v[8:9]
	v_pk_mul_f32 v[18:19], v[18:19], v[4:5]
	ds_read_b64_tr_b16 v[2:3], v84 offset:57344
	ds_read_b64_tr_b16 v[4:5], v84 offset:58624
	ds_read_b64_tr_b16 v[6:7], v84 offset:63744
	s_waitcnt lgkmcnt(3)
	v_mfma_f32_32x32x16_bf16 v[16:31], v[36:39], v[40:43], v[16:31]
	ds_read_b64_tr_b16 v[8:9], v85 offset:3072
	ds_read_b64_tr_b16 v[10:11], v85 offset:3840
	ds_read_b64_tr_b16 v[12:13], v85 offset:6144
	ds_read_b64_tr_b16 v[14:15], v85 offset:6912
	s_cmp_lg_u32 s74, 64
	s_waitcnt vmcnt(16)
	v_mov_b32_e32 v103, v92
	s_waitcnt vmcnt(14)
	v_mov_b32_e32 v101, v93
	s_waitcnt vmcnt(12)
	v_mov_b32_e32 v102, v94
	s_waitcnt vmcnt(10)
	v_mov_b32_e32 v104, v95
	s_waitcnt vmcnt(8)
	v_mov_b32_e32 v105, v96
	s_waitcnt lgkmcnt(2)
	v_mfma_f32_32x32x16_bf16 v[16:31], v[2:5], v[8:11], v[16:31]
	ds_read_b64_tr_b16 v[4:5], v84 offset:62464
	s_waitcnt vmcnt(6)
	v_mov_b32_e32 v106, v97
	s_waitcnt vmcnt(4)
	v_mov_b32_e32 v100, v98
	s_waitcnt vmcnt(2)
	v_mov_b32_e32 v1, v99
	s_mov_b32 s78, s74
	s_waitcnt lgkmcnt(0)
	v_mfma_f32_32x32x16_bf16 v[16:31], v[4:7], v[12:15], v[16:31]
	ds_read_b64_tr_b16 v[2:3], v86 offset:62464
	ds_read_b64_tr_b16 v[4:5], v86 offset:63744
	ds_read_b64_tr_b16 v[6:7], v85 offset:9216
	ds_read_b64_tr_b16 v[8:9], v85 offset:9984
	s_waitcnt lgkmcnt(0)
	v_mfma_f32_32x32x16_bf16 v[16:31], v[2:5], v[6:9], v[16:31]
	s_nop 11
	v_cvt_pk_bf16_f32 v2, v16, v17
	v_cvt_pk_bf16_f32 v3, v18, v19
	v_cvt_pk_bf16_f32 v4, v20, v21
	v_cvt_pk_bf16_f32 v5, v22, v23
	v_cvt_pk_bf16_f32 v6, v24, v25
	v_cvt_pk_bf16_f32 v7, v26, v27
	v_cvt_pk_bf16_f32 v8, v28, v29
	v_cvt_pk_bf16_f32 v9, v30, v31
	ds_write2_b64 v87, v[2:3], v[4:5] offset1:2
	ds_write2_b64 v87, v[6:7], v[8:9] offset0:4 offset1:6
	s_mov_b64 vcc, s[6:7]
	s_cbranch_vccnz .Lhg_w2
	s_waitcnt vmcnt(0)
	s_branch .Lhg_wd
.Lhg_w2:
	s_waitcnt vmcnt(2)
.Lhg_wd:
	v_mov_b64_e32 v[2:3], v[48:49]
	v_mov_b64_e32 v[4:5], v[50:51]
	s_cbranch_scc0 .LBB0_498
